# static priority raise for the younger half (asm guide 6.3/7.4): s_setprio 1 for the O-path waves 4-7 across the GDN chain step loop, reset at phase 4 entry
# baseline (speedup 1.0000x reference)
.LBB0_1019:
	s_and_b32 s12, s59, 4
	s_lshl_b32 s49, s12, 11
	s_lshl_b32 s12, s2, 1
	s_and_b32 s69, s12, 0x300
	s_lshl_b32 s12, s60, 3
	s_and_b32 s70, s12, 0xc0
	s_add_u32 s50, s6, s50
	s_addc_u32 s51, s7, s51
	v_lshlrev_b32_e32 v122, 1, v122
	v_or_b32_e32 v142, s68, v56
	v_lshl_add_u64 v[32:33], s[50:51], 0, v[122:123]
	v_mov_b32_e32 v133, v123
	v_ashrrev_i32_e32 v143, 31, v142
	v_lshl_add_u64 v[44:45], v[32:33], 0, v[132:133]
	v_lshl_add_u64 v[56:57], v[142:143], 1, s[6:7]
	global_load_dwordx4 v[32:35], v[44:45], off
	global_load_dwordx4 v[36:39], v[44:45], off offset:64
	global_load_dwordx4 v[40:43], v[44:45], off offset:128
	s_nop 0
	global_load_dwordx4 v[44:47], v[44:45], off offset:192
	s_nop 0
	global_load_dwordx4 v[48:51], v[52:53], off
	s_lshl_b32 s12, s48, 1
	v_lshl_add_u64 v[56:57], v[56:57], 0, v[132:133]
	s_lshl_b64 s[4:5], s[4:5], 2
	v_lshl_add_u64 v[60:61], v[56:57], 0, s[20:21]
	v_add_co_u32_e32 v56, vcc, s56, v56
	s_add_u32 s4, s65, s4
	v_lshl_add_u64 v[52:53], v[52:53], 0, s[12:13]
	v_addc_co_u32_e32 v57, vcc, 0, v57, vcc
	s_addc_u32 s5, s66, s5
	global_load_dwordx4 v[52:55], v[52:53], off
	s_nop 0
	global_load_dwordx4 v[56:59], v[56:57], off
	s_nop 0
	global_load_dwordx4 v[60:63], v[60:61], off offset:64
	v_lshl_add_u32 v129, v64, 4, 0
	global_load_dword v144, v123, s[4:5]
	s_lshl_b32 s4, s52, 11
	s_and_b32 s4, s4, 0xffffc000
	s_or_b32 s4, s4, s49
	s_ashr_i32 s5, s4, 31
	s_lshl_b64 s[4:5], s[4:5], 10
	s_bfe_u32 s6, s53, 0x20006
	v_sub_u32_e32 v65, v129, v65
	s_or_b32 s4, s4, s69
	v_lshlrev_b32_e32 v64, 12, v64
	v_lshl_add_u32 v131, s6, 5, v65
	v_add_u32_e32 v66, s67, v65
	s_or_b32 s4, s4, s70
	v_lshl_or_b32 v64, s6, 14, v64
	v_lshlrev_b32_e32 v65, 1, v125
	v_or3_b32 v64, s4, v64, v65
	v_mov_b32_e32 v65, s5
	s_waitcnt lgkmcnt(0)
	s_barrier
	v_lshl_add_u64 v[64:65], s[10:11], 0, v[64:65]
	v_lshl_add_u64 v[146:147], v[64:65], 0, s[22:23]
	v_mov_b32_e32 v64, 0
	s_mov_b32 s39, 0
	v_mul_u32_u24_e32 v141, 0x90, v125
	s_or_b32 s67, s38, 3
	s_or_b32 s68, s38, 4
	v_add_u32_e32 v145, v66, v127
	v_mov_b32_e32 v65, v64
	v_mov_b32_e32 v66, v64
	v_mov_b32_e32 v67, v64
	v_mov_b32_e32 v76, v64
	v_mov_b32_e32 v77, v64
	v_mov_b32_e32 v78, v64
	v_mov_b32_e32 v79, v64
	v_readfirstlane_b32 s98, v180
	s_lshr_b32 s98, s98, 6
	s_cmp_lt_u32 s98, 4
	s_cbranch_scc1 .Lchain_prio_skip
	s_setprio 1
.Lchain_prio_skip:
.LBB0_1020:
	s_add_i32 s4, s39, 2
	s_min_u32 s4, s4, 0x7f
	s_or_b32 s4, s4, s38
	s_mul_i32 s6, s4, 0x12000
	s_mul_hi_i32 s5, s4, 0x12000
	s_add_u32 s6, s37, s6
	s_addc_u32 s7, s62, s5
	s_mov_b64 s[10:11], -1
	s_and_b64 vcc, exec, s[42:43]
	s_cbranch_vccz .LBB0_1022
	v_lshl_add_u64 v[68:69], v[136:137], 1, s[6:7]
	v_mov_b32_e32 v133, v123
	v_lshl_add_u64 v[68:69], v[68:69], 0, v[132:133]
	v_lshl_add_u64 v[68:69], v[68:69], 0, s[18:19]
	s_mov_b64 s[10:11], 0

.LBB0_1293:
	s_setprio 0
	v_readlane_b32 s2, v253, 0
	v_readlane_b32 s3, v253, 1
	s_cmp_lt_i32 s2, 5
	s_cselect_b64 s[2:3], -1, 0
	s_and_b64 s[0:1], s[2:3], s[0:1]
	s_andn2_b64 vcc, exec, s[0:1]
	s_cbranch_vccnz .LBB0_1381
	s_mov_b64 s[12:13], s[92:93]
	s_load_dwordx2 s[10:11], s[12:13], 0x120
	s_load_dwordx2 s[14:15], s[12:13], 0x98
	v_mov_b32_e32 v8, v180
	s_waitcnt lgkmcnt(0)
	s_add_u32 s16, s10, 0x3618b200
	s_addc_u32 s17, s11, 0
	s_add_u32 s18, s10, 0x3214b200
	s_addc_u32 s19, s11, 0
	s_cmpk_gt_i32 s94, 0x1ff
	v_readfirstlane_b32 s5, v8
	s_cbranch_scc1 .LBB0_1358
	v_lshlrev_b32_e32 v0, 4, v8
	v_add_u32_e32 v1, 0x2000, v0
	v_ashrrev_i32_e32 v2, 31, v1
	v_lshrrev_b32_e32 v2, 22, v2
	v_add_u32_e32 v2, v1, v2
	v_ashrrev_i32_e32 v2, 10, v2
	v_mul_i32_i24_e32 v3, 0x400, v2
	v_sub_u32_e32 v1, v1, v3
	v_lshrrev_b32_e32 v3, 4, v1
	v_bitop3_b32 v1, v3, v1, 32 bitop3:0x6c
	v_ashrrev_i32_e32 v3, 31, v1
	v_lshrrev_b32_e32 v3, 26, v3
	v_add_u32_e32 v3, v1, v3
	v_lshlrev_b32_e32 v5, 3, v2
	v_ashrrev_i32_e32 v4, 6, v3
	v_and_b32_e32 v5, -16, v5
	v_add_u32_e32 v5, v4, v5
	v_and_b32_e32 v4, 3, v4
	s_mov_b32 s8, 0x1ffffe0
	v_lshrrev_b32_e32 v6, 2, v5
	v_lshlrev_b32_e32 v7, 1, v5
	v_and_b32_e32 v3, 0xc0, v3
	v_and_or_b32 v4, v5, s8, v4
	v_and_b32_e32 v6, 4, v6
	v_and_b32_e32 v7, 24, v7
	v_lshlrev_b32_e32 v2, 5, v2
	v_sub_u32_e32 v1, v1, v3
	v_mov_b32_e32 v3, 1
	v_or3_b32 v4, v4, v6, v7
	s_movk_i32 s9, 0x180
	v_and_b32_e32 v2, 32, v2
	v_ashrrev_i16_sdwa v1, v3, sext(v1) dst_sel:DWORD dst_unused:UNUSED_PAD src0_sel:DWORD src1_sel:BYTE_0
	v_mul_lo_u32 v4, v4, s9
	v_add_u32_sdwa v1, v2, sext(v1) dst_sel:DWORD dst_unused:UNUSED_PAD src0_sel:DWORD src1_sel:WORD_0
	v_mul_lo_u32 v2, v5, s9
	v_add_lshl_u32 v168, v4, v1, 1
	v_add_lshl_u32 v170, v1, v2, 1
	v_bfe_i32 v1, v8, 27, 1
	v_lshrrev_b32_e32 v1, 22, v1
	v_add_u32_e32 v1, v0, v1
	v_and_b32_e32 v1, 0xfffffc00, v1
	v_sub_u32_e32 v0, v0, v1
	v_ashrrev_i32_e32 v2, 31, v8
	v_lshrrev_b32_e32 v1, 4, v0
	v_lshrrev_b32_e32 v2, 26, v2
	v_bitop3_b32 v1, v1, v0, 32 bitop3:0x6c
	v_ashrrev_i32_e32 v0, 31, v0
	v_add_u32_e32 v2, v8, v2
	v_lshrrev_b32_e32 v0, 26, v0
	v_ashrrev_i32_e32 v2, 6, v2
	v_add_u32_e32 v0, v1, v0
	v_lshlrev_b32_e32 v4, 3, v2
	v_ashrrev_i32_e32 v0, 6, v0
	v_and_b32_e32 v4, -16, v4
	s_add_u32 s33, s10, 0x2e00000
	v_add_u32_e32 v4, v0, v4
	s_addc_u32 s40, s11, 0
	s_ashr_i32 s6, s5, 6
	v_and_b32_e32 v5, 3, v0
	v_lshrrev_b32_e32 v6, 2, v4
	v_lshlrev_b32_e32 v7, 1, v4
	v_mul_i32_i24_e32 v0, 64, v0
	s_ashr_i32 s7, s5, 8
	s_lshl_b32 s4, s6, 10
	s_mul_i32 s1, s58, 0x30000
	v_and_or_b32 v5, v4, s8, v5
	v_and_b32_e32 v6, 4, v6
	v_and_b32_e32 v7, 24, v7
	v_lshlrev_b32_e32 v2, 5, v2
	v_sub_u32_e32 v0, v1, v0
	s_mul_hi_i32 s0, s58, 0x30000
	v_or3_b32 v5, v5, v6, v7
	v_and_b32_e32 v2, 32, v2
	v_ashrrev_i16_sdwa v0, v3, sext(v0) dst_sel:DWORD dst_unused:UNUSED_PAD src0_sel:DWORD src1_sel:BYTE_0
	s_add_u32 s8, s33, s1
	v_mul_lo_u32 v5, v5, s9
	v_add_u32_sdwa v0, v2, sext(v0) dst_sel:DWORD dst_unused:UNUSED_PAD src0_sel:DWORD src1_sel:WORD_0
	v_mul_lo_u32 v1, v4, s9
	s_addc_u32 s9, s40, s0
	s_add_i32 s41, s4, 0
	v_add_lshl_u32 v172, v5, v0, 1
	s_add_i32 m0, s41, 0x10000
	v_add_lshl_u32 v174, v0, v1, 1
	global_load_lds_dwordx4 v172, s[8:9]
	s_add_i32 m0, s41, 0x12000
	s_add_u32 s0, s8, 0x18000
	global_load_lds_dwordx4 v168, s[8:9]
	s_addc_u32 s1, s9, 0
	s_add_i32 m0, s41, 0x14000
	v_mov_b32_e32 v177, 0
	global_load_lds_dwordx4 v172, s[0:1]
	s_add_i32 m0, s41, 0x16000
	v_mov_b32_e32 v173, v177
	global_load_lds_dwordx4 v168, s[0:1]
	v_readlane_b32 s0, v253, 37
	s_add_u32 s0, s16, s0
	v_readlane_b32 s1, v253, 36
	s_addc_u32 s1, s17, s1
	s_add_i32 s42, s41, 0x2000
	s_mov_b32 m0, s41
	s_add_u32 s20, s0, 0x18000
	s_addc_u32 s21, s1, 0
	global_load_lds_dwordx4 v174, s[0:1]
	s_mov_b32 m0, s42
	s_add_i32 s43, s41, 0x4000
	global_load_lds_dwordx4 v170, s[0:1]
	s_mov_b32 m0, s43
	s_add_i32 s48, s41, 0x6000
	global_load_lds_dwordx4 v174, s[20:21]
	s_mov_b32 m0, s48
	v_mov_b32_e32 v169, v177
	global_load_lds_dwordx4 v170, s[20:21]
	v_mov_b32_e32 v175, v177
	v_mov_b32_e32 v171, v177
	s_cmp_eq_u32 s7, 1
	v_lshl_add_u64 v[6:7], s[8:9], 0, v[172:173]
	v_lshl_add_u64 v[4:5], s[8:9], 0, v[168:169]
	v_lshl_add_u64 v[0:1], s[0:1], 0, v[174:175]
	s_cselect_b64 s[20:21], -1, 0
	s_cmp_lg_u32 s7, 1
	v_lshl_add_u64 v[2:3], s[0:1], 0, v[170:171]
	s_cbranch_scc1 .LBB0_1297
	s_barrier
